# GEMM K-loops (in-proj and out-proj): each iteration leads with an MFMA on resident fragments, ring arithmetic / fragment reads / LDS-DMA pieces issued in the MFMA shadow, scalar-base DMA addressing
# speedup vs baseline: 1.1275x; 1.0172x over previous
; #define RAW_BARRIER() do { asm volatile("s_waitcnt lgkmcnt(0)" ::: "memory"); __builtin_amdgcn_s_barrier(); } while (0)
; #define GEMM_READ2(A_, B_, FA, FB) asm volatile( \
;         "ds_read_b128 %0, %4\n\tds_read_b128 %1, %4 offset:2048\n\tds_read_b128 %2, %5\n\tds_read_b128 %3, %5 offset:2048" \
;         : "=&v"(FA[0]), "=&v"(FA[1]), "=&v"(FB[0]), "=&v"(FB[1]) : "v"(A_), "v"(B_) : "memory")
; template <int WM, class Epi>
; DI void gemm_mfma(const bf16_t* __restrict__ A, const bf16_t* __restrict__ Bt, int Arows, int Brows, int MT, int NT, unsigned char* smem, int bid, int nb, int wave, Epi epi) {
;     ...
;     auto issue = [&](int kt, int buf) {
; #pragma unroll
;       for (int i = 0; i < NAW; ++i)
;         __builtin_amdgcn_global_load_lds((const unsigned*)(abase + kt * astep + i * 1024 + voff),
;                                          (__attribute__((address_space(3))) unsigned*)(smem + buf * STAGE + (wvu * NAW + i) * 1024), 16, 0, 0);
; #pragma unroll
;       for (int i = 0; i < 2; ++i)
;         __builtin_amdgcn_global_load_lds((const unsigned*)(bbase + kt * bstep + i * 1024 + voff),
;                                          (__attribute__((address_space(3))) unsigned*)(smem + buf * STAGE + A_BYTES + (wvu * 2 + i) * 1024), 16, 0, 0);
;     };
;     ...
; #pragma unroll 1
;     for (int kt = 0; kt < NKT; ++kt) {
;       const int ahead = (NKT - 1 - kt < NST - 2) ? (NKT - 1 - kt) : (NST - 2);
;       if (NI == 4) { if (ahead == 2) asm volatile("s_waitcnt vmcnt(8)" ::: "memory"); else if (ahead == 1) asm volatile("s_waitcnt vmcnt(4)" ::: "memory"); else asm volatile("s_waitcnt vmcnt(0)" ::: "memory"); }
;       else { if (ahead == 1) asm volatile("s_waitcnt vmcnt(6)" ::: "memory"); else asm volatile("s_waitcnt vmcnt(0)" ::: "memory"); }
;       RAW_BARRIER();
;       if (kt + NST - 1 < NKT) issue(kt + NST - 1, (kt + NST - 1) % NST);
;       const unsigned sb = lds0 + (unsigned)((kt % NST) * STAGE);
;       const unsigned a0 = sb + offA0, a1 = sb + offA1, b0 = sb + offB0, b1 = sb + offB1;
;       if constexpr (WM == 4) GEMM_READ4(a0, b0, fa0, fb0); else GEMM_READ2(a0, b0, fa0, fb0);
;       GEMM_MMA(fa1, fb1);
;       if constexpr (WM == 4) { GEMM_WAIT4(fa0, fb0); GEMM_READ4(a1, b1, fa1, fb1); } else { GEMM_WAIT2(fa0, fb0); GEMM_READ2(a1, b1, fa1, fb1); }
;       GEMM_MMA(fa0, fb0);
;     }
.LBB0_169:
	s_waitcnt lgkmcnt(0)
	s_add_i32 s6, s21, -2
	s_cmp_gt_u32 s6, 29
	s_barrier
	s_cbranch_scc1 .LBB0_164
	s_setprio 1
	v_mfma_f32_32x32x16_bf16 v[112:127], v[148:151], v[144:147], v[112:127]
	s_mul_i32 s7, s21, 0xab
	s_bfe_u32 s7, s7, 0x70009
	s_mul_i32 s7, s7, 3
	s_sub_i32 s7, s21, s7
	s_and_b32 s7, s7, 0xff
	s_mulk_i32 s7, 0x6000
	s_add_i32 s25, s7, s9
	s_add_i32 s7, s7, s20
	s_mul_i32 s26, s6, 0xab
	s_bfe_u32 s26, s26, 0x70009
	s_mul_i32 s26, s26, 3
	s_sub_i32 s6, s6, s26
	s_and_b32 s6, s6, 0xff
	s_mulk_i32 s6, 0x6000
	v_add_u32_e32 v160, s6, v159
	v_add_u32_e32 v170, s6, v165
	ds_read_b128 v[196:199], v160
	ds_read_b128 v[200:203], v160 offset:2048
	v_mfma_f32_32x32x16_bf16 v[96:111], v[148:151], v[136:139], v[96:111]
	ds_read_b128 v[204:207], v160 offset:4096
	ds_read_b128 v[208:211], v160 offset:6144
	v_mfma_f32_32x32x16_bf16 v[80:95], v[140:143], v[144:147], v[80:95]
	ds_read_b128 v[212:215], v170
	ds_read_b128 v[216:219], v170 offset:2048
	s_add_u32 s98, s0, 0x8c000
	s_addc_u32 s99, s1, 0
	s_add_u32 s100, s4, 0x2006000
	s_addc_u32 s101, s5, 0
	s_add_i32 m0, s7, 0x4000
	v_mfma_f32_32x32x16_bf16 v[64:79], v[140:143], v[136:139], v[64:79]
	global_load_lds_dwordx4 v154, s[98:99]
	v_add_u32_e32 v160, s6, v164
	v_add_u32_e32 v170, s6, v166
	v_mfma_f32_32x32x16_bf16 v[48:63], v[132:135], v[144:147], v[48:63]
	global_load_lds_dwordx4 v154, s[98:99] offset:1024
	s_mov_b32 m0, s25
	v_mfma_f32_32x32x16_bf16 v[32:47], v[132:135], v[136:139], v[32:47]
	v_mfma_f32_32x32x16_bf16 v[16:31], v[128:131], v[144:147], v[16:31]
	global_load_lds_dwordx4 v154, s[100:101]
	v_mfma_f32_32x32x16_bf16 v[0:15], v[128:131], v[136:139], v[0:15]
	global_load_lds_dwordx4 v154, s[100:101] offset:1024
	s_setprio 0
	s_waitcnt lgkmcnt(0)
	ds_read_b128 v[148:151], v160
	ds_read_b128 v[140:143], v160 offset:2048
	ds_read_b128 v[132:135], v160 offset:4096
	ds_read_b128 v[128:131], v160 offset:6144
	ds_read_b128 v[144:147], v170
	ds_read_b128 v[136:139], v170 offset:2048
	s_setprio 1
	v_mfma_f32_32x32x16_bf16 v[112:127], v[196:199], v[212:215], v[112:127]
	global_load_lds_dwordx4 v154, s[100:101] offset:2048
	v_mfma_f32_32x32x16_bf16 v[96:111], v[196:199], v[216:219], v[96:111]
	v_mfma_f32_32x32x16_bf16 v[80:95], v[200:203], v[212:215], v[80:95]
	global_load_lds_dwordx4 v154, s[100:101] offset:3072
	v_mfma_f32_32x32x16_bf16 v[64:79], v[200:203], v[216:219], v[64:79]
	v_mfma_f32_32x32x16_bf16 v[48:63], v[204:207], v[212:215], v[48:63]
	v_mfma_f32_32x32x16_bf16 v[32:47], v[204:207], v[216:219], v[32:47]
	v_mfma_f32_32x32x16_bf16 v[16:31], v[208:211], v[212:215], v[16:31]
	v_mfma_f32_32x32x16_bf16 v[0:15], v[208:211], v[216:219], v[0:15]
	s_setprio 0
	s_add_u32 s0, s0, 0x46000
	s_addc_u32 s1, s1, 0
	s_add_u32 s4, s4, 0x120000
	s_addc_u32 s5, s5, 0
	s_add_i32 s21, s21, 1
	s_branch .LBB0_165

; #define RAW_BARRIER() do { asm volatile("s_waitcnt lgkmcnt(0)" ::: "memory"); __builtin_amdgcn_s_barrier(); } while (0)
; #define GEMM_READ2(A_, B_, FA, FB) asm volatile( \
;         "ds_read_b128 %0, %4\n\tds_read_b128 %1, %4 offset:2048\n\tds_read_b128 %2, %5\n\tds_read_b128 %3, %5 offset:2048" \
;         : "=&v"(FA[0]), "=&v"(FA[1]), "=&v"(FB[0]), "=&v"(FB[1]) : "v"(A_), "v"(B_) : "memory")
; template <int WM, class Epi>
; DI void gemm_mfma(const bf16_t* __restrict__ A, const bf16_t* __restrict__ Bt, int Arows, int Brows, int MT, int NT, unsigned char* smem, int bid, int nb, int wave, Epi epi) {
;     ...
;     auto issue = [&](int kt, int buf) {
; #pragma unroll
;       for (int i = 0; i < NAW; ++i)
;         __builtin_amdgcn_global_load_lds((const unsigned*)(abase + kt * astep + i * 1024 + voff),
;                                          (__attribute__((address_space(3))) unsigned*)(smem + buf * STAGE + (wvu * NAW + i) * 1024), 16, 0, 0);
; #pragma unroll
;       for (int i = 0; i < 2; ++i)
;         __builtin_amdgcn_global_load_lds((const unsigned*)(bbase + kt * bstep + i * 1024 + voff),
;                                          (__attribute__((address_space(3))) unsigned*)(smem + buf * STAGE + A_BYTES + (wvu * 2 + i) * 1024), 16, 0, 0);
;     };
;     ...
; #pragma unroll 1
;     for (int kt = 0; kt < NKT; ++kt) {
;       const int ahead = (NKT - 1 - kt < NST - 2) ? (NKT - 1 - kt) : (NST - 2);
;       if (NI == 4) { if (ahead == 2) asm volatile("s_waitcnt vmcnt(8)" ::: "memory"); else if (ahead == 1) asm volatile("s_waitcnt vmcnt(4)" ::: "memory"); else asm volatile("s_waitcnt vmcnt(0)" ::: "memory"); }
;       else { if (ahead == 1) asm volatile("s_waitcnt vmcnt(6)" ::: "memory"); else asm volatile("s_waitcnt vmcnt(0)" ::: "memory"); }
;       RAW_BARRIER();
;       if (kt + NST - 1 < NKT) issue(kt + NST - 1, (kt + NST - 1) % NST);
;       const unsigned sb = lds0 + (unsigned)((kt % NST) * STAGE);
;       const unsigned a0 = sb + offA0, a1 = sb + offA1, b0 = sb + offB0, b1 = sb + offB1;
;       if constexpr (WM == 4) GEMM_READ4(a0, b0, fa0, fb0); else GEMM_READ2(a0, b0, fa0, fb0);
;       GEMM_MMA(fa1, fb1);
;       if constexpr (WM == 4) { GEMM_WAIT4(fa0, fb0); GEMM_READ4(a1, b1, fa1, fb1); } else { GEMM_WAIT2(fa0, fb0); GEMM_READ2(a1, b1, fa1, fb1); }
;       GEMM_MMA(fa0, fb0);
;     }
.LBB0_1060:
	s_waitcnt lgkmcnt(0)
	s_add_i32 s8, s29, -2
	s_cmp_gt_u32 s8, 29
	s_barrier
	s_cbranch_scc1 .LBB0_1055
	s_setprio 1
	v_mfma_f32_32x32x16_bf16 v[112:127], v[148:151], v[144:147], v[112:127]
	s_mul_i32 s9, s29, 0xab
	s_bfe_u32 s9, s9, 0x70009
	s_mul_i32 s9, s9, 3
	s_sub_i32 s9, s29, s9
	s_and_b32 s9, s9, 0xff
	s_mulk_i32 s9, 0x6000
	s_add_i32 s30, s9, s27
	s_add_i32 s9, s9, s28
	s_mul_i32 s34, s8, 0xab
	s_bfe_u32 s34, s34, 0x70009
	s_mul_i32 s34, s34, 3
	s_sub_i32 s8, s8, s34
	s_and_b32 s8, s8, 0xff
	s_mulk_i32 s8, 0x6000
	v_add_u32_e32 v216, s8, v157
	v_add_u32_e32 v217, s8, v159
	ds_read_b128 v[168:171], v216
	ds_read_b128 v[196:199], v216 offset:2048
	v_mfma_f32_32x32x16_bf16 v[96:111], v[148:151], v[132:135], v[96:111]
	ds_read_b128 v[200:203], v216 offset:4096
	ds_read_b128 v[204:207], v216 offset:6144
	v_mfma_f32_32x32x16_bf16 v[80:95], v[140:143], v[144:147], v[80:95]
	ds_read_b128 v[208:211], v217
	ds_read_b128 v[212:215], v217 offset:2048
	s_add_u32 s98, s4, 0x11a0000
	s_addc_u32 s99, s5, 0
	s_add_u32 s100, s6, 0x2006000
	s_addc_u32 s101, s7, 0
	s_add_i32 m0, s9, 0x4000
	v_mfma_f32_32x32x16_bf16 v[64:79], v[140:143], v[132:135], v[64:79]
	global_load_lds_dwordx4 v152, s[98:99]
	v_add_u32_e32 v216, s8, v158
	v_add_u32_e32 v217, s8, v164
	v_mfma_f32_32x32x16_bf16 v[48:63], v[136:139], v[144:147], v[48:63]
	global_load_lds_dwordx4 v152, s[98:99] offset:1024
	s_mov_b32 m0, s30
	v_mfma_f32_32x32x16_bf16 v[32:47], v[136:139], v[132:135], v[32:47]
	v_mfma_f32_32x32x16_bf16 v[16:31], v[128:131], v[144:147], v[16:31]
	global_load_lds_dwordx4 v152, s[100:101]
	v_mfma_f32_32x32x16_bf16 v[0:15], v[128:131], v[132:135], v[0:15]
	global_load_lds_dwordx4 v152, s[100:101] offset:1024
	s_setprio 0
	s_waitcnt lgkmcnt(0)
	ds_read_b128 v[148:151], v216
	ds_read_b128 v[140:143], v216 offset:2048
	ds_read_b128 v[136:139], v216 offset:4096
	ds_read_b128 v[128:131], v216 offset:6144
	ds_read_b128 v[144:147], v217
	ds_read_b128 v[132:135], v217 offset:2048
	s_setprio 1
	v_mfma_f32_32x32x16_bf16 v[112:127], v[168:171], v[208:211], v[112:127]
	global_load_lds_dwordx4 v152, s[100:101] offset:2048
	v_mfma_f32_32x32x16_bf16 v[96:111], v[168:171], v[212:215], v[96:111]
	v_mfma_f32_32x32x16_bf16 v[80:95], v[196:199], v[208:211], v[80:95]
	global_load_lds_dwordx4 v152, s[100:101] offset:3072
	v_mfma_f32_32x32x16_bf16 v[64:79], v[196:199], v[212:215], v[64:79]
	v_mfma_f32_32x32x16_bf16 v[48:63], v[200:203], v[208:211], v[48:63]
	v_mfma_f32_32x32x16_bf16 v[32:47], v[200:203], v[212:215], v[32:47]
	v_mfma_f32_32x32x16_bf16 v[16:31], v[204:207], v[208:211], v[16:31]
	v_mfma_f32_32x32x16_bf16 v[0:15], v[204:207], v[212:215], v[0:15]
	s_setprio 0
	s_add_u32 s4, s4, 0x10000
	s_addc_u32 s5, s5, 0
	s_add_u32 s6, s6, 0x120000
	s_addc_u32 s7, s7, 0
	s_add_i32 s29, s29, 1
	s_branch .LBB0_1056
